# attention output stores plain instead of nt (v33 otherwise)
# baseline (speedup 1.0000x reference)
.Latt_ud_done:
	s_lshl_b32 s2, s0, 5
	s_add_i32 s42, s15, s2
	s_mov_b32 s43, 0
	s_waitcnt vmcnt(12)
	v_mov_b32_e32 v132, 0
	v_mfma_f32_16x16x32_bf16 v[236:239], v[0:3], v[48:51], 0
	v_mfma_f32_16x16x32_bf16 v[236:239], v[4:7], v[52:55], v[236:239]
	v_mfma_f32_16x16x32_bf16 v[240:243], v[8:11], v[48:51], 0
	v_mfma_f32_16x16x32_bf16 v[240:243], v[12:15], v[52:55], v[240:243]
	s_nop 7
	v_min_f32_e32 v152, 0x42a00000, v236
	v_min_f32_e32 v153, 0x42a00000, v237
	v_min_f32_e32 v154, 0x42a00000, v238
	v_min_f32_e32 v155, 0x42a00000, v239
	v_mfma_f32_16x16x32_bf16 v[236:239], v[16:19], v[48:51], 0
	v_mfma_f32_16x16x32_bf16 v[236:239], v[20:23], v[52:55], v[236:239]
	v_add_u32_e32 v136, 0x60, v182
	v_med3_i32 v136, v136, 0, s38
	v_lshl_add_u32 v136, v136, 9, v179
	global_load_dwordx4 v[0:3], v136, s[24:25]
	global_load_dwordx4 v[4:7], v136, s[24:25] offset:64
	v_mul_f32_e32 v152, 0x3fb8aa3b, v152
	v_mul_f32_e32 v153, 0x3fb8aa3b, v153
	v_mul_f32_e32 v154, 0x3fb8aa3b, v154
	v_mul_f32_e32 v155, 0x3fb8aa3b, v155
	v_exp_f32_e32 v152, v152
	v_exp_f32_e32 v153, v153
	v_exp_f32_e32 v154, v154
	v_exp_f32_e32 v155, v155
	v_add_u32_e32 v138, 0, v175
	v_add_u32_e32 v139, 1, v175
	v_add_u32_e32 v140, 2, v175
	v_add_u32_e32 v141, 3, v175
	v_cmp_gt_u32_e64 s[70:71], s44, v138
	v_cmp_gt_u32_e64 s[72:73], s44, v139
	v_cmp_gt_u32_e64 s[74:75], s44, v140
	v_cmp_gt_u32_e64 s[76:77], s44, v141
	v_cndmask_b32_e64 v152, 0, v152, s[54:55]
	v_cndmask_b32_e64 v153, 0, v153, s[56:57]
	v_cndmask_b32_e64 v154, 0, v154, s[58:59]
	v_cndmask_b32_e64 v155, 0, v155, s[60:61]
	v_cndmask_b32_e64 v152, 0, v152, s[70:71]
	v_cndmask_b32_e64 v153, 0, v153, s[72:73]
	v_cndmask_b32_e64 v154, 0, v154, s[74:75]
	v_cndmask_b32_e64 v155, 0, v155, s[76:77]
	v_add_f32_e32 v132, v132, v152
	v_add_f32_e32 v132, v132, v153
	v_add_f32_e32 v132, v132, v154
	v_add_f32_e32 v132, v132, v155
	v_cvt_pk_bf16_f32 v112, v152, v153
	v_cvt_pk_bf16_f32 v113, v154, v155
	v_min_f32_e32 v152, 0x42a00000, v240
	v_min_f32_e32 v153, 0x42a00000, v241
	v_min_f32_e32 v154, 0x42a00000, v242
	v_min_f32_e32 v155, 0x42a00000, v243
	v_mfma_f32_16x16x32_bf16 v[240:243], v[24:27], v[48:51], 0
	v_mfma_f32_16x16x32_bf16 v[240:243], v[28:31], v[52:55], v[240:243]
	v_add_u32_e32 v135, 0x70, v182
	v_med3_i32 v135, v135, 0, s38
	v_lshl_add_u32 v135, v135, 9, v179
	global_load_dwordx4 v[8:11], v135, s[24:25]
	global_load_dwordx4 v[12:15], v135, s[24:25] offset:64
	v_mul_f32_e32 v152, 0x3fb8aa3b, v152
	v_mul_f32_e32 v153, 0x3fb8aa3b, v153
	v_mul_f32_e32 v154, 0x3fb8aa3b, v154
	v_mul_f32_e32 v155, 0x3fb8aa3b, v155
	v_exp_f32_e32 v152, v152
	v_exp_f32_e32 v153, v153
	v_exp_f32_e32 v154, v154
	v_exp_f32_e32 v155, v155
	v_add_u32_e32 v138, 16, v175
	v_add_u32_e32 v139, 17, v175
	v_add_u32_e32 v140, 18, v175
	v_add_u32_e32 v141, 19, v175
	v_cmp_gt_u32_e64 s[70:71], s44, v138
	v_cmp_gt_u32_e64 s[72:73], s44, v139
	v_cmp_gt_u32_e64 s[74:75], s44, v140
	v_cmp_gt_u32_e64 s[76:77], s44, v141
	v_cndmask_b32_e64 v152, 0, v152, s[70:71]
	v_cndmask_b32_e64 v153, 0, v153, s[72:73]
	v_cndmask_b32_e64 v154, 0, v154, s[74:75]
	v_cndmask_b32_e64 v155, 0, v155, s[76:77]
	v_add_f32_e32 v132, v132, v152
	v_add_f32_e32 v132, v132, v153
	v_add_f32_e32 v132, v132, v154
	v_add_f32_e32 v132, v132, v155
	v_cvt_pk_bf16_f32 v114, v152, v153
	v_cvt_pk_bf16_f32 v115, v154, v155
	v_min_f32_e32 v152, 0x42a00000, v236
	v_min_f32_e32 v153, 0x42a00000, v237
	v_min_f32_e32 v154, 0x42a00000, v238
	v_min_f32_e32 v155, 0x42a00000, v239
	v_mfma_f32_16x16x32_bf16 v[236:239], v[32:35], v[48:51], 0
	v_mfma_f32_16x16x32_bf16 v[236:239], v[36:39], v[52:55], v[236:239]
	v_add_u32_e32 v136, 0x80, v182
	v_med3_i32 v136, v136, 0, s38
	v_lshl_add_u32 v136, v136, 9, v179
	global_load_dwordx4 v[16:19], v136, s[24:25]
	global_load_dwordx4 v[20:23], v136, s[24:25] offset:64
	v_mul_f32_e32 v152, 0x3fb8aa3b, v152
	v_mul_f32_e32 v153, 0x3fb8aa3b, v153
	v_mul_f32_e32 v154, 0x3fb8aa3b, v154
	v_mul_f32_e32 v155, 0x3fb8aa3b, v155
	v_exp_f32_e32 v152, v152
	v_exp_f32_e32 v153, v153
	v_exp_f32_e32 v154, v154
	v_exp_f32_e32 v155, v155
	v_add_u32_e32 v138, 32, v175
	v_add_u32_e32 v139, 33, v175
	v_add_u32_e32 v140, 34, v175
	v_add_u32_e32 v141, 35, v175
	v_cmp_gt_u32_e64 s[70:71], s44, v138
	v_cmp_gt_u32_e64 s[72:73], s44, v139
	v_cmp_gt_u32_e64 s[74:75], s44, v140
	v_cmp_gt_u32_e64 s[76:77], s44, v141
	v_cndmask_b32_e64 v152, 0, v152, s[70:71]
	v_cndmask_b32_e64 v153, 0, v153, s[72:73]
	v_cndmask_b32_e64 v154, 0, v154, s[74:75]
	v_cndmask_b32_e64 v155, 0, v155, s[76:77]
	v_add_f32_e32 v132, v132, v152
	v_add_f32_e32 v132, v132, v153
	v_add_f32_e32 v132, v132, v154
	v_add_f32_e32 v132, v132, v155
	v_cvt_pk_bf16_f32 v116, v152, v153
	v_cvt_pk_bf16_f32 v117, v154, v155
	v_min_f32_e32 v152, 0x42a00000, v240
	v_min_f32_e32 v153, 0x42a00000, v241
	v_min_f32_e32 v154, 0x42a00000, v242
	v_min_f32_e32 v155, 0x42a00000, v243
	v_mfma_f32_16x16x32_bf16 v[240:243], v[40:43], v[48:51], 0
	v_mfma_f32_16x16x32_bf16 v[240:243], v[44:47], v[52:55], v[240:243]
	v_mul_f32_e32 v152, 0x3fb8aa3b, v152
	v_mul_f32_e32 v153, 0x3fb8aa3b, v153
	v_mul_f32_e32 v154, 0x3fb8aa3b, v154
	v_mul_f32_e32 v155, 0x3fb8aa3b, v155
	v_exp_f32_e32 v152, v152
	v_exp_f32_e32 v153, v153
	v_exp_f32_e32 v154, v154
	v_exp_f32_e32 v155, v155
	v_add_u32_e32 v138, 48, v175
	v_add_u32_e32 v139, 49, v175
	v_add_u32_e32 v140, 50, v175
	v_add_u32_e32 v141, 51, v175
	v_cmp_gt_u32_e64 s[70:71], s44, v138
	v_cmp_gt_u32_e64 s[72:73], s44, v139
	v_cmp_gt_u32_e64 s[74:75], s44, v140
	v_cmp_gt_u32_e64 s[76:77], s44, v141
	v_cndmask_b32_e64 v152, 0, v152, s[70:71]
	v_cndmask_b32_e64 v153, 0, v153, s[72:73]
	v_cndmask_b32_e64 v154, 0, v154, s[74:75]
	v_cndmask_b32_e64 v155, 0, v155, s[76:77]
	v_add_f32_e32 v132, v132, v152
	v_add_f32_e32 v132, v132, v153
	v_add_f32_e32 v132, v132, v154
	v_add_f32_e32 v132, v132, v155
	v_cvt_pk_bf16_f32 v118, v152, v153
	v_cvt_pk_bf16_f32 v119, v154, v155
	v_min_f32_e32 v152, 0x42a00000, v236
	v_min_f32_e32 v153, 0x42a00000, v237
	v_min_f32_e32 v154, 0x42a00000, v238
	v_min_f32_e32 v155, 0x42a00000, v239
	s_waitcnt vmcnt(4)
	v_mfma_f32_16x16x32_bf16 v[236:239], v[0:3], v[48:51], 0
	v_mfma_f32_16x16x32_bf16 v[236:239], v[4:7], v[52:55], v[236:239]
	v_mul_f32_e32 v152, 0x3fb8aa3b, v152
	v_mul_f32_e32 v153, 0x3fb8aa3b, v153
	v_mul_f32_e32 v154, 0x3fb8aa3b, v154
	v_mul_f32_e32 v155, 0x3fb8aa3b, v155
	v_exp_f32_e32 v152, v152
	v_exp_f32_e32 v153, v153
	v_exp_f32_e32 v154, v154
	v_exp_f32_e32 v155, v155
	v_add_u32_e32 v138, 64, v175
	v_add_u32_e32 v139, 0x41, v175
	v_add_u32_e32 v140, 0x42, v175
	v_add_u32_e32 v141, 0x43, v175
	v_cmp_gt_u32_e64 s[70:71], s44, v138
	v_cmp_gt_u32_e64 s[72:73], s44, v139
	v_cmp_gt_u32_e64 s[74:75], s44, v140
	v_cmp_gt_u32_e64 s[76:77], s44, v141
	v_cndmask_b32_e64 v152, 0, v152, s[70:71]
	v_cndmask_b32_e64 v153, 0, v153, s[72:73]
	v_cndmask_b32_e64 v154, 0, v154, s[74:75]
	v_cndmask_b32_e64 v155, 0, v155, s[76:77]
	v_add_f32_e32 v132, v132, v152
	v_add_f32_e32 v132, v132, v153
	v_add_f32_e32 v132, v132, v154
	v_add_f32_e32 v132, v132, v155
	v_cvt_pk_bf16_f32 v120, v152, v153
	v_cvt_pk_bf16_f32 v121, v154, v155
	v_min_f32_e32 v152, 0x42a00000, v240
	v_min_f32_e32 v153, 0x42a00000, v241
	v_min_f32_e32 v154, 0x42a00000, v242
	v_min_f32_e32 v155, 0x42a00000, v243
	s_waitcnt vmcnt(2)
	v_mfma_f32_16x16x32_bf16 v[240:243], v[8:11], v[48:51], 0
	v_mfma_f32_16x16x32_bf16 v[240:243], v[12:15], v[52:55], v[240:243]
	v_mul_f32_e32 v152, 0x3fb8aa3b, v152
	v_mul_f32_e32 v153, 0x3fb8aa3b, v153
	v_mul_f32_e32 v154, 0x3fb8aa3b, v154
	v_mul_f32_e32 v155, 0x3fb8aa3b, v155
	v_exp_f32_e32 v152, v152
	v_exp_f32_e32 v153, v153
	v_exp_f32_e32 v154, v154
	v_exp_f32_e32 v155, v155
	v_add_u32_e32 v138, 0x50, v175
	v_add_u32_e32 v139, 0x51, v175
	v_add_u32_e32 v140, 0x52, v175
	v_add_u32_e32 v141, 0x53, v175
	v_cmp_gt_u32_e64 s[70:71], s44, v138
	v_cmp_gt_u32_e64 s[72:73], s44, v139
	v_cmp_gt_u32_e64 s[74:75], s44, v140
	v_cmp_gt_u32_e64 s[76:77], s44, v141
	v_cndmask_b32_e64 v152, 0, v152, s[70:71]
	v_cndmask_b32_e64 v153, 0, v153, s[72:73]
	v_cndmask_b32_e64 v154, 0, v154, s[74:75]
	v_cndmask_b32_e64 v155, 0, v155, s[76:77]
	v_add_f32_e32 v132, v132, v152
	v_add_f32_e32 v132, v132, v153
	v_add_f32_e32 v132, v132, v154
	v_add_f32_e32 v132, v132, v155
	v_cvt_pk_bf16_f32 v122, v152, v153
	v_cvt_pk_bf16_f32 v123, v154, v155
	v_min_f32_e32 v152, 0x42a00000, v236
	v_min_f32_e32 v153, 0x42a00000, v237
	v_min_f32_e32 v154, 0x42a00000, v238
	v_min_f32_e32 v155, 0x42a00000, v239
	s_waitcnt vmcnt(0)
	v_mfma_f32_16x16x32_bf16 v[236:239], v[16:19], v[48:51], 0
	v_mfma_f32_16x16x32_bf16 v[236:239], v[20:23], v[52:55], v[236:239]
	v_mul_f32_e32 v152, 0x3fb8aa3b, v152
	v_mul_f32_e32 v153, 0x3fb8aa3b, v153
	v_mul_f32_e32 v154, 0x3fb8aa3b, v154
	v_mul_f32_e32 v155, 0x3fb8aa3b, v155
	v_exp_f32_e32 v152, v152
	v_exp_f32_e32 v153, v153
	v_exp_f32_e32 v154, v154
	v_exp_f32_e32 v155, v155
	v_add_u32_e32 v138, 0x60, v175
	v_add_u32_e32 v139, 0x61, v175
	v_add_u32_e32 v140, 0x62, v175
	v_add_u32_e32 v141, 0x63, v175
	v_cmp_gt_u32_e64 s[70:71], s44, v138
	v_cmp_gt_u32_e64 s[72:73], s44, v139
	v_cmp_gt_u32_e64 s[74:75], s44, v140
	v_cmp_gt_u32_e64 s[76:77], s44, v141
	v_cndmask_b32_e64 v152, 0, v152, s[70:71]
	v_cndmask_b32_e64 v153, 0, v153, s[72:73]
	v_cndmask_b32_e64 v154, 0, v154, s[74:75]
	v_cndmask_b32_e64 v155, 0, v155, s[76:77]
	v_add_f32_e32 v132, v132, v152
	v_add_f32_e32 v132, v132, v153
	v_add_f32_e32 v132, v132, v154
	v_add_f32_e32 v132, v132, v155
	v_cvt_pk_bf16_f32 v124, v152, v153
	v_cvt_pk_bf16_f32 v125, v154, v155
	v_min_f32_e32 v152, 0x42a00000, v240
	v_min_f32_e32 v153, 0x42a00000, v241
	v_min_f32_e32 v154, 0x42a00000, v242
	v_min_f32_e32 v155, 0x42a00000, v243
	v_mul_f32_e32 v152, 0x3fb8aa3b, v152
	v_mul_f32_e32 v153, 0x3fb8aa3b, v153
	v_mul_f32_e32 v154, 0x3fb8aa3b, v154
	v_mul_f32_e32 v155, 0x3fb8aa3b, v155
	v_exp_f32_e32 v152, v152
	v_exp_f32_e32 v153, v153
	v_exp_f32_e32 v154, v154
	v_exp_f32_e32 v155, v155
	v_add_u32_e32 v138, 0x70, v175
	v_add_u32_e32 v139, 0x71, v175
	v_add_u32_e32 v140, 0x72, v175
	v_add_u32_e32 v141, 0x73, v175
	v_cmp_gt_u32_e64 s[70:71], s44, v138
	v_cmp_gt_u32_e64 s[72:73], s44, v139
	v_cmp_gt_u32_e64 s[74:75], s44, v140
	v_cmp_gt_u32_e64 s[76:77], s44, v141
	v_cndmask_b32_e64 v152, 0, v152, s[70:71]
	v_cndmask_b32_e64 v153, 0, v153, s[72:73]
	v_cndmask_b32_e64 v154, 0, v154, s[74:75]
	v_cndmask_b32_e64 v155, 0, v155, s[76:77]
	v_add_f32_e32 v132, v132, v152
	v_add_f32_e32 v132, v132, v153
	v_add_f32_e32 v132, v132, v154
	v_add_f32_e32 v132, v132, v155
	v_cvt_pk_bf16_f32 v126, v152, v153
	v_cvt_pk_bf16_f32 v127, v154, v155
	v_min_f32_e32 v152, 0x42a00000, v236
	v_min_f32_e32 v153, 0x42a00000, v237
	v_min_f32_e32 v154, 0x42a00000, v238
	v_min_f32_e32 v155, 0x42a00000, v239
	v_mul_f32_e32 v152, 0x3fb8aa3b, v152
	v_mul_f32_e32 v153, 0x3fb8aa3b, v153
	v_mul_f32_e32 v154, 0x3fb8aa3b, v154
	v_mul_f32_e32 v155, 0x3fb8aa3b, v155
	v_exp_f32_e32 v152, v152
	v_exp_f32_e32 v153, v153
	v_exp_f32_e32 v154, v154
	v_exp_f32_e32 v155, v155
	v_add_u32_e32 v138, 0x80, v175
	v_add_u32_e32 v139, 0x81, v175
	v_add_u32_e32 v140, 0x82, v175
	v_add_u32_e32 v141, 0x83, v175
	v_cmp_gt_u32_e64 s[70:71], s44, v138
	v_cmp_gt_u32_e64 s[72:73], s44, v139
	v_cmp_gt_u32_e64 s[74:75], s44, v140
	v_cmp_gt_u32_e64 s[76:77], s44, v141
	v_cndmask_b32_e64 v152, 0, v152, s[62:63]
	v_cndmask_b32_e64 v153, 0, v153, s[64:65]
	v_cndmask_b32_e64 v154, 0, v154, s[66:67]
	v_cndmask_b32_e64 v155, 0, v155, s[68:69]
	v_cndmask_b32_e64 v152, 0, v152, s[70:71]
	v_cndmask_b32_e64 v153, 0, v153, s[72:73]
	v_cndmask_b32_e64 v154, 0, v154, s[74:75]
	v_cndmask_b32_e64 v155, 0, v155, s[76:77]
	v_add_f32_e32 v132, v132, v152
	v_add_f32_e32 v132, v132, v153
	v_add_f32_e32 v132, v132, v154
	v_add_f32_e32 v132, v132, v155
	v_cvt_pk_bf16_f32 v128, v152, v153
	v_cvt_pk_bf16_f32 v129, v154, v155
	v_add_u32_e32 v134, s42, v160
	v_add_u32_e32 v134, s43, v134
	v_subrev_u32_e32 v135, s15, v134
	v_lshrrev_b32_e32 v136, 4, v135
	v_add_u32_e32 v136, v136, v135
	v_mad_u32_u24 v176, v136, s79, v161
	v_lshl_add_u32 v177, v135, 2, s80
	s_sub_i32 s2, s42, 64
	v_add_u32_e32 v178, s2, v169
	v_and_b32_e32 v135, 3, v134
	v_lshlrev_b32_e32 v135, s13, v135
	v_lshrrev_b32_e32 v136, 2, v134
	v_add_u32_e32 v135, v135, v136
	v_lshl_add_u32 v135, v135, 7, v161
	global_load_dwordx4 v[48:51], v135, s[18:19]
	global_load_dwordx4 v[52:55], v135, s[18:19] offset:64
	v_add_u32_e32 v137, 16, v134
	v_and_b32_e32 v135, 3, v137
	v_lshlrev_b32_e32 v135, s13, v135
	v_lshrrev_b32_e32 v136, 2, v137
	v_add_u32_e32 v135, v135, v136
	v_lshl_add_u32 v135, v135, 7, v161
	global_load_dwordx4 v[56:59], v135, s[18:19]
	global_load_dwordx4 v[60:63], v135, s[18:19] offset:64
	v_subrev_u32_e32 v134, 64, v134
	v_and_b32_e32 v137, 3, v134
	v_lshlrev_b32_e32 v137, s13, v137
	v_bfe_u32 v135, v134, 2, 2
	v_add_u32_e32 v137, v137, v135
	v_lshl_add_u32 v183, v137, 7, v161
	v_ashrrev_i32_e32 v252, 4, v134
	v_med3_i32 v136, v252, 0, s14
	v_lshl_add_u32 v136, v136, 9, v183
	global_load_dwordx4 v[0:3], v136, s[20:21]
	global_load_dwordx4 v[4:7], v136, s[20:21] offset:64
	v_add_u32_e32 v135, 1, v252
	v_med3_i32 v135, v135, 0, s14
	v_lshl_add_u32 v135, v135, 9, v183
	global_load_dwordx4 v[8:11], v135, s[20:21]
	global_load_dwordx4 v[12:15], v135, s[20:21] offset:64
	v_add_u32_e32 v136, 2, v252
	v_med3_i32 v136, v136, 0, s14
	v_lshl_add_u32 v136, v136, 9, v183
	global_load_dwordx4 v[16:19], v136, s[20:21]
	global_load_dwordx4 v[20:23], v136, s[20:21] offset:64
	v_add_u32_e32 v135, 3, v252
	v_med3_i32 v135, v135, 0, s14
	v_lshl_add_u32 v135, v135, 9, v183
	global_load_dwordx4 v[24:27], v135, s[20:21]
	global_load_dwordx4 v[28:31], v135, s[20:21] offset:64
	v_add_u32_e32 v136, 4, v252
	v_med3_i32 v136, v136, 0, s14
	v_lshl_add_u32 v136, v136, 9, v183
	global_load_dwordx4 v[32:35], v136, s[20:21]
	global_load_dwordx4 v[36:39], v136, s[20:21] offset:64
	v_add_u32_e32 v135, 5, v252
	v_med3_i32 v135, v135, 0, s14
	v_lshl_add_u32 v135, v135, 9, v183
	global_load_dwordx4 v[40:43], v135, s[20:21]
	global_load_dwordx4 v[44:47], v135, s[20:21] offset:64
	ds_bpermute_b32 v142, v167, v132
	s_waitcnt lgkmcnt(0)
	v_add_f32_e32 v132, v132, v142
	ds_bpermute_b32 v142, v168, v132
	s_waitcnt lgkmcnt(0)
	v_add_f32_e32 v132, v132, v142
	s_waitcnt vmcnt(16)
	ds_write_b128 v165, v[64:67]
	ds_write_b128 v165, v[68:71] offset:1152
	ds_write_b128 v165, v[72:75] offset:2304
	ds_write_b128 v165, v[76:79] offset:3456
	s_waitcnt lgkmcnt(0)
	ds_read_b64_tr_b16 v[236:237], v166
	ds_read_b64_tr_b16 v[238:239], v166 offset:2304
	ds_read_b64_tr_b16 v[240:241], v166 offset:32
	ds_read_b64_tr_b16 v[242:243], v166 offset:2336
	ds_read_b64_tr_b16 v[244:245], v166 offset:64
	ds_read_b64_tr_b16 v[246:247], v166 offset:2368
	ds_read_b64_tr_b16 v[248:249], v166 offset:96
	ds_read_b64_tr_b16 v[250:251], v166 offset:2400
	s_waitcnt lgkmcnt(0)
	s_add_i32 s2, s40, 32
	v_add_u32_e32 v138, s2, v164
	v_lshlrev_b32_e32 v138, 4, v138
	v_add_u32_e32 v138, s41, v138
	v_and_b32_e32 v139, 3, v138
	v_lshlrev_b32_e32 v139, s39, v139
	v_bfe_u32 v140, v138, 2, 2
	v_add_u32_e32 v139, v139, v140
	v_lshl_add_u32 v139, v139, 7, v162
	v_ashrrev_i32_e32 v138, 4, v138
	v_med3_i32 v138, v138, 0, s38
	v_lshl_add_u32 v138, v138, 9, v139
	global_load_dwordx4 v[64:67], v138, s[26:27]
	s_add_i32 s2, s40, 40
	v_add_u32_e32 v138, s2, v164
	v_lshlrev_b32_e32 v138, 4, v138
	v_add_u32_e32 v138, s41, v138
	v_and_b32_e32 v139, 3, v138
	v_lshlrev_b32_e32 v139, s39, v139
	v_bfe_u32 v140, v138, 2, 2
	v_add_u32_e32 v139, v139, v140
	v_lshl_add_u32 v139, v139, 7, v162
	v_ashrrev_i32_e32 v138, 4, v138
	v_med3_i32 v138, v138, 0, s38
	v_lshl_add_u32 v138, v138, 9, v139
	global_load_dwordx4 v[68:71], v138, s[26:27]
	s_add_i32 s2, s40, 48
	v_add_u32_e32 v138, s2, v164
	v_lshlrev_b32_e32 v138, 4, v138
	v_add_u32_e32 v138, s41, v138
	v_and_b32_e32 v139, 3, v138
	v_lshlrev_b32_e32 v139, s39, v139
	v_bfe_u32 v140, v138, 2, 2
	v_add_u32_e32 v139, v139, v140
	v_lshl_add_u32 v139, v139, 7, v162
	v_ashrrev_i32_e32 v138, 4, v138
	v_med3_i32 v138, v138, 0, s38
	v_lshl_add_u32 v138, v138, 9, v139
	global_load_dwordx4 v[72:75], v138, s[26:27]
	s_add_i32 s2, s40, 56
	v_add_u32_e32 v138, s2, v164
	v_lshlrev_b32_e32 v138, 4, v138
	v_add_u32_e32 v138, s41, v138
	v_and_b32_e32 v139, 3, v138
	v_lshlrev_b32_e32 v139, s39, v139
	v_bfe_u32 v140, v138, 2, 2
	v_add_u32_e32 v139, v139, v140
	v_lshl_add_u32 v139, v139, 7, v162
	v_ashrrev_i32_e32 v138, 4, v138
	v_med3_i32 v138, v138, 0, s38
	v_lshl_add_u32 v138, v138, 9, v139
	global_load_dwordx4 v[76:79], v138, s[26:27]
	ds_write_b128 v165, v[80:83]
	ds_write_b128 v165, v[84:87] offset:1152
	ds_write_b128 v165, v[88:91] offset:2304
	ds_write_b128 v165, v[92:95] offset:3456
	v_mfma_f32_16x16x32_bf16 v[204:207], v[236:239], v[112:115], 0
	v_mfma_f32_16x16x32_bf16 v[208:211], v[240:243], v[112:115], 0
	v_mfma_f32_16x16x32_bf16 v[212:215], v[244:247], v[112:115], 0
	v_mfma_f32_16x16x32_bf16 v[216:219], v[248:251], v[112:115], 0
	s_waitcnt lgkmcnt(0)
	ds_read_b64_tr_b16 v[236:237], v166
	ds_read_b64_tr_b16 v[238:239], v166 offset:2304
	ds_read_b64_tr_b16 v[240:241], v166 offset:32
	ds_read_b64_tr_b16 v[242:243], v166 offset:2336
	ds_read_b64_tr_b16 v[244:245], v166 offset:64
	ds_read_b64_tr_b16 v[246:247], v166 offset:2368
	ds_read_b64_tr_b16 v[248:249], v166 offset:96
	ds_read_b64_tr_b16 v[250:251], v166 offset:2400
	s_waitcnt lgkmcnt(0)
	s_add_i32 s2, s40, 64
	v_add_u32_e32 v138, s2, v164
	v_lshlrev_b32_e32 v138, 4, v138
	v_add_u32_e32 v138, s41, v138
	v_and_b32_e32 v139, 3, v138
	v_lshlrev_b32_e32 v139, s39, v139
	v_bfe_u32 v140, v138, 2, 2
	v_add_u32_e32 v139, v139, v140
	v_lshl_add_u32 v139, v139, 7, v162
	v_ashrrev_i32_e32 v138, 4, v138
	v_med3_i32 v138, v138, 0, s38
	v_lshl_add_u32 v138, v138, 9, v139
	global_load_dwordx4 v[80:83], v138, s[26:27]
	s_add_i32 s2, s40, 72
	v_add_u32_e32 v138, s2, v164
	v_lshlrev_b32_e32 v138, 4, v138
	v_add_u32_e32 v138, s41, v138
	v_and_b32_e32 v139, 3, v138
	v_lshlrev_b32_e32 v139, s39, v139
	v_bfe_u32 v140, v138, 2, 2
	v_add_u32_e32 v139, v139, v140
	v_lshl_add_u32 v139, v139, 7, v162
	v_ashrrev_i32_e32 v138, 4, v138
	v_med3_i32 v138, v138, 0, s38
	v_lshl_add_u32 v138, v138, 9, v139
	global_load_dwordx4 v[84:87], v138, s[26:27]
	ds_write_b128 v165, v[96:99]
	ds_write_b128 v165, v[100:103] offset:1152
	ds_write_b128 v165, v[104:107] offset:2304
	ds_write_b128 v165, v[108:111] offset:3456
	v_mfma_f32_16x16x32_bf16 v[204:207], v[236:239], v[116:119], v[204:207]
	v_mfma_f32_16x16x32_bf16 v[208:211], v[240:243], v[116:119], v[208:211]
	v_mfma_f32_16x16x32_bf16 v[212:215], v[244:247], v[116:119], v[212:215]
	v_mfma_f32_16x16x32_bf16 v[216:219], v[248:251], v[116:119], v[216:219]
	s_waitcnt lgkmcnt(0)
	ds_read_b64_tr_b16 v[236:237], v166
	ds_read_b64_tr_b16 v[238:239], v166 offset:2304
	ds_read_b64_tr_b16 v[240:241], v166 offset:32
	ds_read_b64_tr_b16 v[242:243], v166 offset:2336
	ds_read_b64_tr_b16 v[244:245], v166 offset:64
	ds_read_b64_tr_b16 v[246:247], v166 offset:2368
	ds_read_b64_tr_b16 v[248:249], v166 offset:96
	ds_read_b64_tr_b16 v[250:251], v166 offset:2400
	s_waitcnt lgkmcnt(0)
	s_waitcnt vmcnt(2)
	ds_write_b128 v165, v[64:67]
	ds_write_b128 v165, v[68:71] offset:1152
	ds_write_b128 v165, v[72:75] offset:2304
	ds_write_b128 v165, v[76:79] offset:3456
	v_mfma_f32_16x16x32_bf16 v[204:207], v[236:239], v[120:123], v[204:207]
	v_mfma_f32_16x16x32_bf16 v[208:211], v[240:243], v[120:123], v[208:211]
	v_mfma_f32_16x16x32_bf16 v[212:215], v[244:247], v[120:123], v[212:215]
	v_mfma_f32_16x16x32_bf16 v[216:219], v[248:251], v[120:123], v[216:219]
	s_waitcnt lgkmcnt(0)
	ds_read_b64_tr_b16 v[236:237], v166
	ds_read_b64_tr_b16 v[238:239], v166 offset:2304
	ds_read_b64_tr_b16 v[240:241], v166 offset:32
	ds_read_b64_tr_b16 v[242:243], v166 offset:2336
	ds_read_b64_tr_b16 v[244:245], v166 offset:64
	ds_read_b64_tr_b16 v[246:247], v166 offset:2368
	ds_read_b64_tr_b16 v[248:249], v166 offset:96
	ds_read_b64_tr_b16 v[250:251], v166 offset:2400
	s_waitcnt lgkmcnt(0)
	s_waitcnt vmcnt(0)
	ds_write_b128 v165, v[80:83]
	ds_write_b128 v165, v[84:87] offset:1152
	v_mfma_f32_16x16x32_bf16 v[204:207], v[236:239], v[124:127], v[204:207]
	v_mfma_f32_16x16x32_bf16 v[208:211], v[240:243], v[124:127], v[208:211]
	v_mfma_f32_16x16x32_bf16 v[212:215], v[244:247], v[124:127], v[212:215]
	v_mfma_f32_16x16x32_bf16 v[216:219], v[248:251], v[124:127], v[216:219]
	s_waitcnt lgkmcnt(0)
	ds_read_b64_tr_b16 v[236:237], v166
	ds_read_b64_tr_b16 v[238:239], v166 offset:2304
	ds_read_b64_tr_b16 v[240:241], v166 offset:32
	ds_read_b64_tr_b16 v[242:243], v166 offset:2336
	ds_read_b64_tr_b16 v[244:245], v166 offset:64
	ds_read_b64_tr_b16 v[246:247], v166 offset:2368
	ds_read_b64_tr_b16 v[248:249], v166 offset:96
	ds_read_b64_tr_b16 v[250:251], v166 offset:2400
	s_waitcnt lgkmcnt(0)
	v_mfma_f32_16x16x32_bf16 v[204:207], v[236:239], v[128:131], v[204:207]
	v_mfma_f32_16x16x32_bf16 v[208:211], v[240:243], v[128:131], v[208:211]
	v_mfma_f32_16x16x32_bf16 v[212:215], v[244:247], v[128:131], v[212:215]
	v_mfma_f32_16x16x32_bf16 v[216:219], v[248:251], v[128:131], v[216:219]
	s_add_i32 s2, s42, -64
	v_add_u32_e32 v138, s2, v164
	v_add_u32_e32 v138, s43, v138
	v_and_b32_e32 v139, 3, v138
	v_lshlrev_b32_e32 v139, s13, v139
	v_bfe_u32 v140, v138, 2, 2
	v_add_u32_e32 v139, v139, v140
	v_lshl_add_u32 v139, v139, 7, v162
	v_ashrrev_i32_e32 v138, 4, v138
	v_med3_i32 v138, v138, 0, s14
	v_lshl_add_u32 v138, v138, 9, v139
	global_load_dwordx4 v[64:67], v138, s[22:23]
	s_add_i32 s2, s42, -56
	v_add_u32_e32 v138, s2, v164
	v_add_u32_e32 v138, s43, v138
	v_and_b32_e32 v139, 3, v138
	v_lshlrev_b32_e32 v139, s13, v139
	v_bfe_u32 v140, v138, 2, 2
	v_add_u32_e32 v139, v139, v140
	v_lshl_add_u32 v139, v139, 7, v162
	v_ashrrev_i32_e32 v138, 4, v138
	v_med3_i32 v138, v138, 0, s14
	v_lshl_add_u32 v138, v138, 9, v139
	global_load_dwordx4 v[68:71], v138, s[22:23]
	s_add_i32 s2, s42, -48
	v_add_u32_e32 v138, s2, v164
	v_add_u32_e32 v138, s43, v138
	v_and_b32_e32 v139, 3, v138
	v_lshlrev_b32_e32 v139, s13, v139
	v_bfe_u32 v140, v138, 2, 2
	v_add_u32_e32 v139, v139, v140
	v_lshl_add_u32 v139, v139, 7, v162
	v_ashrrev_i32_e32 v138, 4, v138
	v_med3_i32 v138, v138, 0, s14
	v_lshl_add_u32 v138, v138, 9, v139
	global_load_dwordx4 v[72:75], v138, s[22:23]
	s_add_i32 s2, s42, -40
	v_add_u32_e32 v138, s2, v164
	v_add_u32_e32 v138, s43, v138
	v_and_b32_e32 v139, 3, v138
	v_lshlrev_b32_e32 v139, s13, v139
	v_bfe_u32 v140, v138, 2, 2
	v_add_u32_e32 v139, v139, v140
	v_lshl_add_u32 v139, v139, 7, v162
	v_ashrrev_i32_e32 v138, 4, v138
	v_med3_i32 v138, v138, 0, s14
	v_lshl_add_u32 v138, v138, 9, v139
	global_load_dwordx4 v[76:79], v138, s[22:23]
	s_add_i32 s2, s42, -32
	v_add_u32_e32 v138, s2, v164
	v_add_u32_e32 v138, s43, v138
	v_and_b32_e32 v139, 3, v138
	v_lshlrev_b32_e32 v139, s13, v139
	v_bfe_u32 v140, v138, 2, 2
	v_add_u32_e32 v139, v139, v140
	v_lshl_add_u32 v139, v139, 7, v162
	v_ashrrev_i32_e32 v138, 4, v138
	v_med3_i32 v138, v138, 0, s14
	v_lshl_add_u32 v138, v138, 9, v139
	global_load_dwordx4 v[80:83], v138, s[22:23]
	s_add_i32 s2, s42, -24
	v_add_u32_e32 v138, s2, v164
	v_add_u32_e32 v138, s43, v138
	v_and_b32_e32 v139, 3, v138
	v_lshlrev_b32_e32 v139, s13, v139
	v_bfe_u32 v140, v138, 2, 2
	v_add_u32_e32 v139, v139, v140
	v_lshl_add_u32 v139, v139, 7, v162
	v_ashrrev_i32_e32 v138, 4, v138
	v_med3_i32 v138, v138, 0, s14
	v_lshl_add_u32 v138, v138, 9, v139
	global_load_dwordx4 v[84:87], v138, s[22:23]
	s_add_i32 s2, s42, -16
	v_add_u32_e32 v138, s2, v164
	v_add_u32_e32 v138, s43, v138
	v_and_b32_e32 v139, 3, v138
	v_lshlrev_b32_e32 v139, s13, v139
	v_bfe_u32 v140, v138, 2, 2
	v_add_u32_e32 v139, v139, v140
	v_lshl_add_u32 v139, v139, 7, v162
	v_ashrrev_i32_e32 v138, 4, v138
	v_med3_i32 v138, v138, 0, s14
	v_lshl_add_u32 v138, v138, 9, v139
	global_load_dwordx4 v[88:91], v138, s[22:23]
	s_add_i32 s2, s42, -8
	v_add_u32_e32 v138, s2, v164
	v_add_u32_e32 v138, s43, v138
	v_and_b32_e32 v139, 3, v138
	v_lshlrev_b32_e32 v139, s13, v139
	v_bfe_u32 v140, v138, 2, 2
	v_add_u32_e32 v139, v139, v140
	v_lshl_add_u32 v139, v139, 7, v162
	v_ashrrev_i32_e32 v138, 4, v138
	v_med3_i32 v138, v138, 0, s14
	v_lshl_add_u32 v138, v138, 9, v139
	global_load_dwordx4 v[92:95], v138, s[22:23]
	s_add_i32 s2, s42, 0
	v_add_u32_e32 v138, s2, v164
	v_add_u32_e32 v138, s43, v138
	v_and_b32_e32 v139, 3, v138
	v_lshlrev_b32_e32 v139, s13, v139
	v_bfe_u32 v140, v138, 2, 2
	v_add_u32_e32 v139, v139, v140
	v_lshl_add_u32 v139, v139, 7, v162
	v_ashrrev_i32_e32 v138, 4, v138
	v_med3_i32 v138, v138, 0, s14
	v_lshl_add_u32 v138, v138, 9, v139
	global_load_dwordx4 v[96:99], v138, s[22:23]
	s_add_i32 s2, s42, 8
	v_add_u32_e32 v138, s2, v164
	v_add_u32_e32 v138, s43, v138
	v_and_b32_e32 v139, 3, v138
	v_lshlrev_b32_e32 v139, s13, v139
	v_bfe_u32 v140, v138, 2, 2
	v_add_u32_e32 v139, v139, v140
	v_lshl_add_u32 v139, v139, 7, v162
	v_ashrrev_i32_e32 v138, 4, v138
	v_med3_i32 v138, v138, 0, s14
	v_lshl_add_u32 v138, v138, 9, v139
	global_load_dwordx4 v[100:103], v138, s[22:23]
	s_add_i32 s2, s42, 16
	v_add_u32_e32 v138, s2, v164
	v_add_u32_e32 v138, s43, v138
	v_and_b32_e32 v139, 3, v138
	v_lshlrev_b32_e32 v139, s13, v139
	v_bfe_u32 v140, v138, 2, 2
	v_add_u32_e32 v139, v139, v140
	v_lshl_add_u32 v139, v139, 7, v162
	v_ashrrev_i32_e32 v138, 4, v138
	v_med3_i32 v138, v138, 0, s14
	v_lshl_add_u32 v138, v138, 9, v139
	global_load_dwordx4 v[104:107], v138, s[22:23]
	s_add_i32 s2, s42, 24
	v_add_u32_e32 v138, s2, v164
	v_add_u32_e32 v138, s43, v138
	v_and_b32_e32 v139, 3, v138
	v_lshlrev_b32_e32 v139, s13, v139
	v_bfe_u32 v140, v138, 2, 2
	v_add_u32_e32 v139, v139, v140
	v_lshl_add_u32 v139, v139, 7, v162
	v_ashrrev_i32_e32 v138, 4, v138
	v_med3_i32 v138, v138, 0, s14
	v_lshl_add_u32 v138, v138, 9, v139
	global_load_dwordx4 v[108:111], v138, s[22:23]
	ds_read_b128 v[236:239], v173 offset:0
	ds_read_b128 v[240:243], v173 offset:64
	ds_read_b128 v[244:247], v173 offset:128
	ds_read_b128 v[248:251], v173 offset:192
	ds_read_b32 v142, v174 offset:0
	s_waitcnt lgkmcnt(0)
	v_add_f32_e32 v204, v236, v204
	v_add_f32_e32 v205, v237, v205
	v_add_f32_e32 v206, v238, v206
	v_add_f32_e32 v207, v239, v207
	v_add_f32_e32 v208, v240, v208
	v_add_f32_e32 v209, v241, v209
	v_add_f32_e32 v210, v242, v210
	v_add_f32_e32 v211, v243, v211
	v_add_f32_e32 v212, v244, v212
	v_add_f32_e32 v213, v245, v213
	v_add_f32_e32 v214, v246, v214
	v_add_f32_e32 v215, v247, v215
	v_add_f32_e32 v216, v248, v216
	v_add_f32_e32 v217, v249, v217
	v_add_f32_e32 v218, v250, v218
	v_add_f32_e32 v219, v251, v219
	v_add_f32_e32 v132, v142, v132
	ds_write_b128 v173, v[204:207] offset:0
	ds_write_b128 v173, v[208:211] offset:64
	ds_write_b128 v173, v[212:215] offset:128
	ds_write_b128 v173, v[216:219] offset:192
	ds_write_b32 v174, v132 offset:0
	s_waitcnt lgkmcnt(0)
	s_barrier
	ds_read_b128 v[204:207], v170
	ds_read_b128 v[208:211], v170 offset:16
	ds_read_b128 v[212:215], v170 offset:32
	ds_read_b128 v[216:219], v170 offset:48
	ds_read_b128 v[220:223], v170 offset:64
	ds_read_b128 v[224:227], v170 offset:80
	ds_read_b128 v[228:231], v170 offset:96
	ds_read_b128 v[232:235], v170 offset:112
	ds_read_b32 v142, v171
	s_lshl_b32 s2, s35, 11
	s_lshl_b32 s3, s36, 7
	s_add_u32 s2, s2, s3
	s_add_u32 s90, s6, s2
	s_addc_u32 s91, s7, 0
	s_waitcnt lgkmcnt(0)
	v_div_scale_f32 v143, s[30:31], v142, v142, 1.0
	v_rcp_f32_e32 v147, v143
	v_div_scale_f32 v134, vcc, 1.0, v142, 1.0
	v_fma_f32 v135, -v143, v147, 1.0
	v_fmac_f32_e32 v147, v135, v147
	v_mul_f32_e32 v135, v134, v147
	v_fma_f32 v136, -v143, v135, v134
	v_fmac_f32_e32 v135, v136, v147
	v_fma_f32 v143, -v143, v135, v134
	v_div_fmas_f32 v143, v143, v147, v135
	v_div_fixup_f32 v142, v143, v142, 1.0
	v_mul_f32_e32 v204, v142, v204
	v_mul_f32_e32 v205, v142, v205
	v_mul_f32_e32 v206, v142, v206
	v_mul_f32_e32 v207, v142, v207
	v_mul_f32_e32 v208, v142, v208
	v_mul_f32_e32 v209, v142, v209
	v_mul_f32_e32 v210, v142, v210
	v_mul_f32_e32 v211, v142, v211
	v_mul_f32_e32 v212, v142, v212
	v_mul_f32_e32 v213, v142, v213
	v_mul_f32_e32 v214, v142, v214
	v_mul_f32_e32 v215, v142, v215
	v_mul_f32_e32 v216, v142, v216
	v_mul_f32_e32 v217, v142, v217
	v_mul_f32_e32 v218, v142, v218
	v_mul_f32_e32 v219, v142, v219
	v_mul_f32_e32 v220, v142, v220
	v_mul_f32_e32 v221, v142, v221
	v_mul_f32_e32 v222, v142, v222
	v_mul_f32_e32 v223, v142, v223
	v_mul_f32_e32 v224, v142, v224
	v_mul_f32_e32 v225, v142, v225
	v_mul_f32_e32 v226, v142, v226
	v_mul_f32_e32 v227, v142, v227
	v_mul_f32_e32 v228, v142, v228
	v_mul_f32_e32 v229, v142, v229
	v_mul_f32_e32 v230, v142, v230
	v_mul_f32_e32 v231, v142, v231
	v_mul_f32_e32 v232, v142, v232
	v_mul_f32_e32 v233, v142, v233
	v_mul_f32_e32 v234, v142, v234
	v_mul_f32_e32 v235, v142, v235
	v_cvt_pk_bf16_f32 v112, v204, v205
	v_cvt_pk_bf16_f32 v113, v206, v207
	v_cvt_pk_bf16_f32 v114, v208, v209
	v_cvt_pk_bf16_f32 v115, v210, v211
	v_cvt_pk_bf16_f32 v116, v212, v213
	v_cvt_pk_bf16_f32 v117, v214, v215
	v_cvt_pk_bf16_f32 v118, v216, v217
	v_cvt_pk_bf16_f32 v119, v218, v219
	v_cvt_pk_bf16_f32 v120, v220, v221
	v_cvt_pk_bf16_f32 v121, v222, v223
	v_cvt_pk_bf16_f32 v122, v224, v225
	v_cvt_pk_bf16_f32 v123, v226, v227
	v_cvt_pk_bf16_f32 v124, v228, v229
	v_cvt_pk_bf16_f32 v125, v230, v231
	v_cvt_pk_bf16_f32 v126, v232, v233
	v_cvt_pk_bf16_f32 v127, v234, v235
	global_store_dwordx4 v172, v[112:115], s[90:91]
	global_store_dwordx4 v172, v[116:119], s[90:91] offset:16
	global_store_dwordx4 v172, v[120:123], s[90:91] offset:32
	global_store_dwordx4 v172, v[124:127], s[90:91] offset:48
	s_barrier
	s_cmp_eq_u32 s37, 0
	s_cbranch_scc1 .Latt_unit
	s_waitcnt vmcnt(0)
	s_branch .LBB0_365
